# ssd_pass2 epilogue: 15 of the 16 group-norm weight loads issued right after the transpose barrier (about 250 instructions ahead of first use)
# baseline (speedup 1.0000x reference)
.LBB0_220:
	s_waitcnt vmcnt(9)
	v_add_u32_e32 v0, s19, v169
	v_ashrrev_i32_e32 v1, 31, v0
	v_readlane_b32 s0, v251, 24
	v_lshlrev_b64 v[108:109], 12, v[0:1]
	v_readlane_b32 s1, v251, 25
	s_ashr_i32 s35, s34, 31
	v_readlane_b32 s40, v254, 20
	v_lshl_add_u64 v[0:1], s[0:1], 0, v[108:109]
	s_lshl_b32 s28, s17, 1
	s_lshl_b64 s[0:1], s[34:35], 2
	v_readlane_b32 s50, v254, 30
	v_lshl_add_u64 v[0:1], v[0:1], 0, s[28:29]
	v_mov_b32_e32 v133, v157
	v_readlane_b32 s51, v254, 31
	s_add_u32 s0, s50, s0
	v_lshl_add_u64 v[0:1], v[0:1], 0, v[132:133]
	s_addc_u32 s1, s51, s1
	global_load_dword v110, v157, s[0:1]
	global_load_dwordx4 v[28:31], v[0:1], off
	global_load_dwordx4 v[24:27], v[0:1], off offset:128
	global_load_dwordx4 v[20:23], v[0:1], off offset:256
	global_load_dwordx4 v[16:19], v[0:1], off offset:384
	global_load_dwordx4 v[12:15], v[0:1], off offset:512
	global_load_dwordx4 v[8:11], v[0:1], off offset:640
	global_load_dwordx4 v[4:7], v[0:1], off offset:768
	s_nop 0
	global_load_dwordx4 v[0:3], v[0:1], off offset:896
	v_cmp_lt_i32_e32 vcc, v188, v187
	v_readlane_b32 s0, v253, 62
	s_mov_b32 s56, 0x800000
	v_readlane_b32 s52, v254, 32
	v_add3_u32 v112, s0, v173, v137
	ds_read2_b64 v[104:107], v112 offset1:4
	v_add_u32_e32 v113, 0x1000, v112
	v_add_u32_e32 v118, 0x1800, v112
	s_lshl_b32 s0, s20, 2
	s_add_i32 s0, s0, 16
	s_waitcnt vmcnt(10) lgkmcnt(0)
	v_lshlrev_b32_e32 v32, 16, v104
	v_readlane_b32 s53, v254, 33
	v_readlane_b32 s8, v251, 51
	v_readlane_b32 s9, v251, 52
	v_readlane_b32 s72, v254, 41
	v_readlane_b32 s54, v254, 34
	v_readlane_b32 s55, v254, 35
	v_readlane_b32 s70, v254, 39
	v_readlane_b32 s73, v254, 42
	v_readlane_b32 s74, v254, 44
	v_readlane_b32 s76, v254, 46
	v_readlane_b32 s78, v254, 48
	v_readlane_b32 s82, v254, 52
	v_readlane_b32 s60, v254, 54
	v_readlane_b32 s62, v254, 56
	v_readlane_b32 s64, v254, 58
	v_readlane_b32 s66, v254, 60
	s_movk_i32 s68, 0x2040
	v_readlane_b32 s57, v254, 36
	v_readlane_b32 s58, v254, 37
	v_readlane_b32 s59, v254, 38
	v_readlane_b32 s71, v254, 40
	v_readlane_b32 s69, v254, 43
	v_readlane_b32 s75, v254, 45
	v_readlane_b32 s77, v254, 47
	v_readlane_b32 s79, v254, 49
	v_readlane_b32 s80, v254, 50
	v_readlane_b32 s81, v254, 51
	v_readlane_b32 s83, v254, 53
	v_readlane_b32 s61, v254, 55
	v_readlane_b32 s63, v254, 57
	v_readlane_b32 s65, v254, 59
	v_readlane_b32 s67, v254, 61
	s_movk_i32 s73, 0xf5
	s_movk_i32 s55, 0xfff
	s_mov_b32 s54, 0xf0c0
	v_readlane_b32 s41, v254, 21
	v_readlane_b32 s42, v254, 22
	v_readlane_b32 s43, v254, 23
	v_readlane_b32 s44, v254, 24
	v_readlane_b32 s45, v254, 25
	v_readlane_b32 s46, v254, 26
	v_readlane_b32 s47, v254, 27
	v_readlane_b32 s48, v254, 28
	v_readlane_b32 s49, v254, 29
	s_waitcnt vmcnt(8)
	v_fma_f32 v111, v110, v32, v40
	v_and_b32_e32 v32, 0xffff0000, v104
	v_fma_f32 v104, v110, v32, v41
	v_lshlrev_b32_e32 v32, 16, v105
	v_fma_f32 v42, v110, v32, v42
	v_and_b32_e32 v32, 0xffff0000, v105
	v_add_u32_e32 v105, 0x800, v112
	ds_read2_b64 v[34:37], v105 offset0:32 offset1:36
	ds_read2_b64 v[38:41], v113 offset0:64 offset1:68
	v_fmac_f32_e32 v43, v110, v32
	ds_read2_b64 v[114:117], v105 offset0:40 offset1:44
	s_waitcnt lgkmcnt(2)
	v_lshlrev_b32_e32 v32, 16, v34
	v_fma_f32 v48, v110, v32, v48
	v_and_b32_e32 v32, 0xffff0000, v34
	v_fma_f32 v49, v110, v32, v49
	v_lshlrev_b32_e32 v32, 16, v35
	v_fma_f32 v50, v110, v32, v50
	v_and_b32_e32 v32, 0xffff0000, v35
	v_fmac_f32_e32 v51, v110, v32
	s_waitcnt lgkmcnt(1)
	v_lshlrev_b32_e32 v32, 16, v38
	v_fma_f32 v44, v110, v32, v44
	v_and_b32_e32 v32, 0xffff0000, v38
	v_fma_f32 v38, v110, v32, v45
	v_lshlrev_b32_e32 v32, 16, v39
	v_fma_f32 v45, v110, v32, v46
	v_and_b32_e32 v32, 0xffff0000, v39
	v_fmac_f32_e32 v47, v110, v32
	ds_read2_b64 v[32:35], v118 offset0:96 offset1:100
	ds_read2_b64 v[118:121], v118 offset0:104 offset1:108
	s_waitcnt lgkmcnt(1)
	v_lshlrev_b32_e32 v46, 16, v33
	v_fma_f32 v46, v110, v46, v54
	v_and_b32_e32 v33, 0xffff0000, v33
	v_and_b32_e32 v54, 0xffff0000, v107
	v_lshlrev_b32_e32 v39, 16, v32
	v_fmac_f32_e32 v55, v110, v33
	v_lshlrev_b32_e32 v33, 16, v106
	v_fmac_f32_e32 v59, v110, v54
	v_lshlrev_b32_e32 v54, 16, v36
	v_and_b32_e32 v36, 0xffff0000, v36
	v_fma_f32 v39, v110, v39, v52
	v_fma_f32 v33, v110, v33, v56
	v_and_b32_e32 v52, 0xffff0000, v106
	v_fma_f32 v56, v110, v36, v61
	v_lshlrev_b32_e32 v36, 16, v37
	v_and_b32_e32 v32, 0xffff0000, v32
	v_fma_f32 v52, v110, v52, v57
	v_fma_f32 v57, v110, v36, v62
	v_and_b32_e32 v36, 0xffff0000, v37
	v_fma_f32 v32, v110, v32, v53
	v_lshlrev_b32_e32 v53, 16, v107
	v_fmac_f32_e32 v63, v110, v36
	v_lshlrev_b32_e32 v36, 16, v40
	v_fma_f32 v53, v110, v53, v58
	v_fma_f32 v58, v110, v36, v64
	v_and_b32_e32 v36, 0xffff0000, v40
	v_fma_f32 v40, v110, v36, v65
	v_lshlrev_b32_e32 v36, 16, v41
	v_fma_f32 v54, v110, v54, v60
	v_fma_f32 v60, v110, v36, v66
	v_and_b32_e32 v36, 0xffff0000, v41
	v_fmac_f32_e32 v67, v110, v36
	v_lshlrev_b32_e32 v36, 16, v34
	v_and_b32_e32 v34, 0xffff0000, v34
	v_fma_f32 v61, v110, v34, v81
	v_lshlrev_b32_e32 v34, 16, v35
	v_fma_f32 v62, v110, v34, v82
	v_and_b32_e32 v34, 0xffff0000, v35
	v_fma_f32 v41, v110, v36, v80
	v_fmac_f32_e32 v83, v110, v34
	ds_read2_b64 v[34:37], v112 offset0:8 offset1:12
	v_and_b32_e32 v66, 0xffff0000, v114
	v_fma_f32 v66, v110, v66, v73
	v_and_b32_e32 v73, 0xffff0000, v115
	v_and_b32_e32 v80, 0xffff0000, v116
	s_waitcnt lgkmcnt(0)
	v_lshlrev_b32_e32 v65, 16, v35
	v_fma_f32 v65, v110, v65, v78
	v_lshlrev_b32_e32 v78, 16, v37
	v_fma_f32 v78, v110, v78, v90
	v_and_b32_e32 v37, 0xffff0000, v37
	v_and_b32_e32 v90, 0xffff0000, v121
	v_and_b32_e32 v35, 0xffff0000, v35
	v_fmac_f32_e32 v91, v110, v37
	v_lshlrev_b32_e32 v37, 16, v116
	v_fmac_f32_e32 v103, v110, v90
	v_lshl_add_u32 v90, v171, 2, s0
	s_movk_i32 s0, 0x2040
	v_fmac_f32_e32 v79, v110, v35
	v_lshlrev_b32_e32 v35, 16, v114
	v_fma_f32 v37, v110, v37, v92
	v_mad_u32_u24 v92, v172, s0, v90
	v_fma_f32 v35, v110, v35, v72
	v_lshlrev_b32_e32 v72, 16, v115
	ds_read2_b64 v[112:115], v113 offset0:72 offset1:76
	s_waitcnt lgkmcnt(0)
	s_barrier
	ds_write2_b32 v92, v111, v48 offset1:16
	v_add_u32_e32 v48, 0x800, v92
	ds_write2_b32 v48, v104, v49 offset0:4 offset1:20
	v_add_u32_e32 v49, 0x1000, v92
	ds_write2_b32 v49, v42, v50 offset0:8 offset1:24
	v_add_u32_e32 v42, 0x1800, v92
	ds_write2_b32 v42, v43, v51 offset0:12 offset1:28
	ds_write2_b32 v92, v44, v39 offset0:32 offset1:48
	ds_write2_b32 v48, v38, v32 offset0:36 offset1:52
	ds_write2_b32 v49, v45, v46 offset0:40 offset1:56
	ds_write2_b32 v42, v47, v55 offset0:44 offset1:60
	v_add_u32_e32 v32, 0x8000, v92
	ds_write2_b32 v32, v33, v54 offset0:64 offset1:80
	v_add_u32_e32 v33, 0x8800, v92
	v_add_u32_e32 v38, 0x9000, v92
	v_add_u32_e32 v39, 0x9800, v92
	ds_write2_b32 v33, v52, v56 offset0:68 offset1:84
	ds_write2_b32 v38, v53, v57 offset0:72 offset1:88
	ds_write2_b32 v39, v59, v63 offset0:76 offset1:92
	ds_write2_b32 v32, v58, v41 offset0:96 offset1:112
	ds_write2_b32 v33, v40, v61 offset0:100 offset1:116
	ds_write2_b32 v38, v60, v62 offset0:104 offset1:120
	ds_write2_b32 v39, v67, v83 offset0:108 offset1:124
	v_mov_b32_e32 v32, 0x10200
	v_lshlrev_b32_e32 v64, 16, v34
	v_mad_u32_u24 v32, v172, s0, v32
	v_fma_f32 v64, v110, v64, v76
	v_add_u32_e32 v33, v90, v32
	ds_write_b32 v33, v64
	v_mov_b32_e32 v33, 0x10a10
	v_and_b32_e32 v34, 0xffff0000, v34
	v_mad_u32_u24 v33, v172, s0, v33
	v_fma_f32 v34, v110, v34, v77
	v_add_u32_e32 v38, v90, v33
	ds_write_b32 v38, v34
	v_mov_b32_e32 v34, 0x11220
	v_mad_u32_u24 v34, v172, s0, v34
	v_add_u32_e32 v38, v90, v34
	ds_write_b32 v38, v65
	v_mov_b32_e32 v38, 0x11a30
	v_mad_u32_u24 v38, v172, s0, v38
	v_fmac_f32_e32 v75, v110, v73
	v_lshlrev_b32_e32 v73, 16, v112
	v_fma_f32 v80, v110, v80, v93
	v_add_u32_e32 v93, 64, v90
	v_add_u32_e32 v39, v90, v38
	v_fma_f32 v68, v110, v73, v68
	v_and_b32_e32 v73, 0xffff0000, v112
	ds_write_b32 v39, v79
	v_add_u32_e32 v39, v93, v32
	v_fma_f32 v69, v110, v73, v69
	v_lshlrev_b32_e32 v73, 16, v113
	ds_write_b32 v39, v35
	v_add_u32_e32 v35, v93, v33
	v_fma_f32 v72, v110, v72, v74
	v_fma_f32 v70, v110, v73, v70
	v_and_b32_e32 v73, 0xffff0000, v113
	ds_write_b32 v35, v66
	v_add_u32_e32 v35, v93, v34
	v_fmac_f32_e32 v71, v110, v73
	v_lshlrev_b32_e32 v73, 16, v118
	v_add_u32_e32 v43, 0x80, v90
	v_add_u32_e32 v50, 0xc0, v90
	ds_write_b32 v35, v72
	v_add_u32_e32 v35, v93, v38
	v_fma_f32 v73, v110, v73, v84
	v_and_b32_e32 v74, 0xffff0000, v118
	ds_write_b32 v35, v75
	v_add_u32_e32 v35, v43, v32
	v_add_u32_e32 v32, v50, v32
	v_fma_f32 v74, v110, v74, v85
	v_lshlrev_b32_e32 v76, 16, v119
	ds_write_b32 v32, v73
	v_add_u32_e32 v32, v50, v33
	v_fma_f32 v76, v110, v76, v86
	v_and_b32_e32 v77, 0xffff0000, v119
	ds_write_b32 v32, v74
	v_add_u32_e32 v32, v50, v34
	v_fmac_f32_e32 v87, v110, v77
	ds_write_b32 v32, v76
	v_add_u32_e32 v32, v50, v38
	ds_write_b32 v32, v87
	v_mov_b32_e32 v32, 0x18300
	v_lshlrev_b32_e32 v77, 16, v36
	v_mad_u32_u24 v32, v172, s0, v32
	v_fma_f32 v77, v110, v77, v88
	ds_write_b32 v35, v68
	v_add_u32_e32 v35, v43, v33
	v_add_u32_e32 v33, v90, v32
	ds_write_b32 v33, v77
	v_mov_b32_e32 v33, 0x18b10
	v_and_b32_e32 v36, 0xffff0000, v36
	v_mad_u32_u24 v33, v172, s0, v33
	v_fma_f32 v36, v110, v36, v89
	ds_write_b32 v35, v69
	v_add_u32_e32 v35, v43, v34
	v_add_u32_e32 v34, v90, v33
	ds_write_b32 v34, v36
	v_mov_b32_e32 v34, 0x19320
	ds_write_b32 v35, v70
	v_add_u32_e32 v35, v43, v38
	v_mad_u32_u24 v34, v172, s0, v34
	ds_write_b32 v35, v71
	v_add_u32_e32 v35, v90, v34
	ds_write_b32 v35, v78
	v_mad_u32_u24 v35, v172, s0, v198
	v_add_u32_e32 v36, v90, v35
	ds_write_b32 v36, v91
	v_add_u32_e32 v36, v93, v32
	v_lshlrev_b32_e32 v81, 16, v117
	ds_write_b32 v36, v37
	v_add_u32_e32 v36, v93, v33
	v_fma_f32 v81, v110, v81, v94
	v_and_b32_e32 v82, 0xffff0000, v117
	v_and_b32_e32 v86, 0xffff0000, v115
	ds_write_b32 v36, v80
	v_add_u32_e32 v36, v93, v34
	v_fmac_f32_e32 v95, v110, v82
	v_fmac_f32_e32 v99, v110, v86
	v_lshlrev_b32_e32 v86, 16, v120
	ds_write_b32 v36, v81
	v_add_u32_e32 v36, v93, v35
	v_fma_f32 v86, v110, v86, v100
	v_and_b32_e32 v88, 0xffff0000, v120
	ds_write_b32 v36, v95
	v_add_u32_e32 v36, v43, v32
	v_add_u32_e32 v32, v50, v32
	v_lshlrev_b32_e32 v82, 16, v114
	v_fma_f32 v88, v110, v88, v101
	v_lshlrev_b32_e32 v89, 16, v121
	ds_write_b32 v32, v86
	v_add_u32_e32 v32, v50, v33
	v_fma_f32 v82, v110, v82, v96
	v_and_b32_e32 v84, 0xffff0000, v114
	v_fma_f32 v89, v110, v89, v102
	ds_write_b32 v32, v88
	v_add_u32_e32 v32, v50, v34
	v_fma_f32 v84, v110, v84, v97
	v_lshlrev_b32_e32 v85, 16, v115
	ds_write_b32 v36, v82
	v_add_u32_e32 v36, v43, v33
	ds_write_b32 v32, v89
	v_add_u32_e32 v32, v50, v35
	s_movk_i32 s0, 0x810
	v_fma_f32 v85, v110, v85, v98
	ds_write_b32 v36, v84
	v_add_u32_e32 v36, v43, v34
	ds_write_b32 v32, v103
	v_mul_lo_u32 v33, v169, s0
	v_lshlrev_b32_e32 v32, 2, v166
	ds_write_b32 v36, v85
	v_add_u32_e32 v36, v43, v35
	v_add3_u32 v76, 16, v33, v32
	ds_write_b32 v36, v99
	s_waitcnt lgkmcnt(0)
	s_barrier
	ds_read_b128 v[34:37], v76
	ds_read_b128 v[38:41], v76 offset:16
	s_waitcnt vmcnt(0)
	s_lshl_b32 s2, s17, 2
	s_add_u32 s2, s52, s2
	s_addc_u32 s3, s53, 0
	global_load_dwordx4 v[204:207], v32, s[2:3] offset:16
	global_load_dwordx4 v[208:211], v32, s[2:3]
	global_load_dwordx4 v[212:215], v32, s[2:3] offset:272
	global_load_dwordx4 v[216:219], v32, s[2:3] offset:256
	global_load_dwordx4 v[220:223], v32, s[2:3] offset:528
	global_load_dwordx4 v[224:227], v32, s[2:3] offset:512
	global_load_dwordx4 v[228:231], v32, s[2:3] offset:784
	global_load_dwordx4 v[232:235], v32, s[2:3] offset:768
	global_load_dwordx4 v[236:239], v32, s[2:3] offset:1040
	global_load_dwordx4 v[240:243], v32, s[2:3] offset:1024
	global_load_dwordx4 v[146:149], v32, s[2:3] offset:1296
	global_load_dwordx4 v[150:153], v32, s[2:3] offset:1280
	global_load_dwordx4 v[168:171], v32, s[2:3] offset:1552
	global_load_dwordx4 v[172:175], v32, s[2:3] offset:1536
	global_load_dwordx4 v[176:179], v32, s[2:3] offset:1808
	v_lshlrev_b32_e32 v33, 16, v28
	v_and_b32_e32 v28, 0xffff0000, v28
	v_lshlrev_b32_e32 v42, 16, v29
	s_waitcnt lgkmcnt(1)
	v_mul_f32_e32 v72, v35, v28
	v_mul_f32_e32 v73, v34, v33
	v_mul_f32_e32 v77, v72, v72
	v_and_b32_e32 v29, 0xffff0000, v29
	v_mul_f32_e32 v71, v36, v42
	v_fmac_f32_e32 v77, v73, v73
	v_lshlrev_b32_e32 v43, 16, v30
	v_and_b32_e32 v30, 0xffff0000, v30
	v_lshlrev_b32_e32 v44, 16, v31
	v_and_b32_e32 v31, 0xffff0000, v31
	v_mul_f32_e32 v70, v37, v29
	v_fmac_f32_e32 v77, v71, v71
	s_waitcnt lgkmcnt(0)
	v_mul_f32_e32 v69, v38, v43
	v_mul_f32_e32 v68, v39, v30
	v_mul_f32_e32 v65, v41, v31
	v_fmac_f32_e32 v77, v70, v70
	ds_read_b128 v[28:31], v76 offset:256
	ds_read_b128 v[34:37], v76 offset:272
	v_fmac_f32_e32 v77, v69, v69
	v_mul_f32_e32 v67, v40, v44
	v_fmac_f32_e32 v77, v68, v68
	v_fmac_f32_e32 v77, v67, v67
	v_lshlrev_b32_e32 v33, 16, v24
	v_fmac_f32_e32 v77, v65, v65
	v_and_b32_e32 v24, 0xffff0000, v24
	s_waitcnt lgkmcnt(1)
	v_mul_f32_e32 v66, v28, v33
	v_lshlrev_b32_e32 v38, 16, v25
	v_mul_f32_e32 v63, v29, v24
	v_fmac_f32_e32 v77, v66, v66
	v_and_b32_e32 v25, 0xffff0000, v25
	v_mul_f32_e32 v60, v30, v38
	v_fmac_f32_e32 v77, v63, v63
	v_lshlrev_b32_e32 v39, 16, v26
	v_and_b32_e32 v26, 0xffff0000, v26
	v_lshlrev_b32_e32 v40, 16, v27
	v_and_b32_e32 v27, 0xffff0000, v27
	v_mul_f32_e32 v56, v31, v25
	v_fmac_f32_e32 v77, v60, v60
	s_waitcnt lgkmcnt(0)
	v_mul_f32_e32 v51, v34, v39
	v_mul_f32_e32 v45, v35, v26
	v_mul_f32_e32 v35, v37, v27
	v_fmac_f32_e32 v77, v56, v56
	ds_read_b128 v[24:27], v76 offset:512
	ds_read_b128 v[28:31], v76 offset:528
	v_fmac_f32_e32 v77, v51, v51
	v_mul_f32_e32 v40, v36, v40
	v_fmac_f32_e32 v77, v45, v45
	v_fmac_f32_e32 v77, v40, v40
	v_lshlrev_b32_e32 v33, 16, v20
	v_fmac_f32_e32 v77, v35, v35
	v_and_b32_e32 v20, 0xffff0000, v20
	s_waitcnt lgkmcnt(1)
	v_mul_f32_e32 v64, v24, v33
	v_lshlrev_b32_e32 v34, 16, v21
	v_mul_f32_e32 v61, v25, v20
	v_fmac_f32_e32 v77, v64, v64
	v_and_b32_e32 v21, 0xffff0000, v21
	v_mul_f32_e32 v57, v26, v34
	v_fmac_f32_e32 v77, v61, v61
	v_lshlrev_b32_e32 v36, 16, v22
	v_and_b32_e32 v22, 0xffff0000, v22
	v_lshlrev_b32_e32 v37, 16, v23
	v_and_b32_e32 v23, 0xffff0000, v23
	v_mul_f32_e32 v52, v27, v21
	v_fmac_f32_e32 v77, v57, v57
	s_waitcnt lgkmcnt(0)
	v_mul_f32_e32 v46, v28, v36
	v_mul_f32_e32 v41, v29, v22
	v_mul_f32_e32 v36, v30, v37
	v_mul_f32_e32 v30, v31, v23
	v_fmac_f32_e32 v77, v52, v52
	ds_read_b128 v[20:23], v76 offset:768
	ds_read_b128 v[24:27], v76 offset:784
	v_fmac_f32_e32 v77, v46, v46
	v_fmac_f32_e32 v77, v41, v41
	v_fmac_f32_e32 v77, v36, v36
	v_lshlrev_b32_e32 v28, 16, v16
	v_fmac_f32_e32 v77, v30, v30
	v_and_b32_e32 v16, 0xffff0000, v16
	s_waitcnt lgkmcnt(1)
	v_mul_f32_e32 v62, v20, v28
	v_lshlrev_b32_e32 v29, 16, v17
	v_mul_f32_e32 v58, v21, v16
	v_fmac_f32_e32 v77, v62, v62
	v_and_b32_e32 v17, 0xffff0000, v17
	v_mul_f32_e32 v53, v22, v29
	v_fmac_f32_e32 v77, v58, v58
	v_lshlrev_b32_e32 v31, 16, v18
	v_and_b32_e32 v18, 0xffff0000, v18
	v_lshlrev_b32_e32 v33, 16, v19
	v_and_b32_e32 v19, 0xffff0000, v19
	v_mul_f32_e32 v47, v23, v17
	v_fmac_f32_e32 v77, v53, v53
	s_waitcnt lgkmcnt(0)
	v_mul_f32_e32 v42, v24, v31
	v_mul_f32_e32 v37, v25, v18
	v_mul_f32_e32 v27, v27, v19
	v_fmac_f32_e32 v77, v47, v47
	ds_read_b128 v[16:19], v76 offset:1024
	ds_read_b128 v[20:23], v76 offset:1040
	v_fmac_f32_e32 v77, v42, v42
	v_mul_f32_e32 v31, v26, v33
	v_fmac_f32_e32 v77, v37, v37
	v_fmac_f32_e32 v77, v31, v31
	v_lshlrev_b32_e32 v24, 16, v12
	v_fmac_f32_e32 v77, v27, v27
	v_and_b32_e32 v12, 0xffff0000, v12
	s_waitcnt lgkmcnt(1)
	v_mul_f32_e32 v59, v16, v24
	v_lshlrev_b32_e32 v25, 16, v13
	v_mul_f32_e32 v54, v17, v12
	v_fmac_f32_e32 v77, v59, v59
	v_and_b32_e32 v13, 0xffff0000, v13
	v_mul_f32_e32 v48, v18, v25
	v_fmac_f32_e32 v77, v54, v54
	v_lshlrev_b32_e32 v26, 16, v14
	v_and_b32_e32 v14, 0xffff0000, v14
	v_lshlrev_b32_e32 v28, 16, v15
	v_and_b32_e32 v15, 0xffff0000, v15
	v_mul_f32_e32 v43, v19, v13
	v_fmac_f32_e32 v77, v48, v48
	s_waitcnt lgkmcnt(0)
	v_mul_f32_e32 v38, v20, v26
	v_mul_f32_e32 v33, v21, v14
	v_mul_f32_e32 v24, v23, v15
	v_fmac_f32_e32 v77, v43, v43
	ds_read_b128 v[12:15], v76 offset:1280
	ds_read_b128 v[16:19], v76 offset:1296
	v_fmac_f32_e32 v77, v38, v38
	v_mul_f32_e32 v28, v22, v28
	v_fmac_f32_e32 v77, v33, v33
	v_fmac_f32_e32 v77, v28, v28
	v_lshlrev_b32_e32 v20, 16, v8
	v_fmac_f32_e32 v77, v24, v24
	v_and_b32_e32 v8, 0xffff0000, v8
	s_waitcnt lgkmcnt(1)
	v_mul_f32_e32 v55, v12, v20
	v_lshlrev_b32_e32 v21, 16, v9
	v_mul_f32_e32 v49, v13, v8
	v_fmac_f32_e32 v77, v55, v55
	v_and_b32_e32 v9, 0xffff0000, v9
	v_mul_f32_e32 v44, v14, v21
	v_fmac_f32_e32 v77, v49, v49
	v_lshlrev_b32_e32 v22, 16, v10
	v_and_b32_e32 v10, 0xffff0000, v10
	v_lshlrev_b32_e32 v23, 16, v11
	v_and_b32_e32 v11, 0xffff0000, v11
	v_mul_f32_e32 v39, v15, v9
	v_fmac_f32_e32 v77, v44, v44
	s_waitcnt lgkmcnt(0)
	v_mul_f32_e32 v34, v16, v22
	v_mul_f32_e32 v29, v17, v10
	v_mul_f32_e32 v25, v18, v23
	v_mul_f32_e32 v23, v19, v11
	v_fmac_f32_e32 v77, v39, v39
	ds_read_b128 v[8:11], v76 offset:1536
	ds_read_b128 v[12:15], v76 offset:1552
	v_fmac_f32_e32 v77, v34, v34
	v_fmac_f32_e32 v77, v29, v29
	v_fmac_f32_e32 v77, v25, v25
	v_lshlrev_b32_e32 v16, 16, v4
	v_fmac_f32_e32 v77, v23, v23
	v_and_b32_e32 v4, 0xffff0000, v4
	s_waitcnt lgkmcnt(1)
	v_mul_f32_e32 v50, v8, v16
	v_lshlrev_b32_e32 v17, 16, v5
	v_and_b32_e32 v5, 0xffff0000, v5
	v_lshlrev_b32_e32 v18, 16, v6
	v_and_b32_e32 v6, 0xffff0000, v6
	v_lshlrev_b32_e32 v74, 16, v7
	v_and_b32_e32 v7, 0xffff0000, v7
	v_mul_f32_e32 v26, v9, v4
	v_fmac_f32_e32 v77, v50, v50
	v_mul_f32_e32 v22, v10, v17
	v_mul_f32_e32 v21, v11, v5
	s_waitcnt lgkmcnt(0)
	v_mul_f32_e32 v20, v12, v18
	v_mul_f32_e32 v19, v13, v6
	v_mul_f32_e32 v18, v14, v74
	v_mul_f32_e32 v17, v15, v7
	v_fmac_f32_e32 v77, v26, v26
	v_lshlrev_b32_e32 v4, 16, v0
	v_and_b32_e32 v5, 0xffff0000, v0
	v_lshlrev_b32_e32 v6, 16, v1
	v_and_b32_e32 v7, 0xffff0000, v1
	v_lshlrev_b32_e32 v8, 16, v2
	v_and_b32_e32 v9, 0xffff0000, v2
	v_lshlrev_b32_e32 v74, 16, v3
	v_and_b32_e32 v75, 0xffff0000, v3
	ds_read_b128 v[0:3], v76 offset:1792
	v_fmac_f32_e32 v77, v22, v22
	v_fmac_f32_e32 v77, v21, v21
	v_fmac_f32_e32 v77, v20, v20
	v_fmac_f32_e32 v77, v19, v19
	v_fmac_f32_e32 v77, v18, v18
	s_waitcnt lgkmcnt(0)
	v_pk_mul_f32 v[14:15], v[0:1], v[4:5]
	v_fmac_f32_e32 v77, v17, v17
	v_pk_mul_f32 v[0:1], v[14:15], v[14:15]
	v_pk_mul_f32 v[12:13], v[2:3], v[6:7]
	v_add_f32_e32 v0, v77, v0
	v_add_f32_e32 v4, v0, v1
	v_pk_mul_f32 v[0:1], v[12:13], v[12:13]
	s_lshl_b32 s0, s17, 2
	v_add_f32_e32 v0, v4, v0
	v_add_f32_e32 v4, v0, v1
	ds_read_b128 v[0:3], v76 offset:1808
	s_add_u32 s0, s52, s0
	s_addc_u32 s1, s53, 0
	s_waitcnt lgkmcnt(0)
	v_pk_mul_f32 v[10:11], v[0:1], v[8:9]
	s_nop 0
	v_pk_mul_f32 v[0:1], v[10:11], v[10:11]
	v_pk_mul_f32 v[8:9], v[2:3], v[74:75]
	v_add_f32_e32 v0, v4, v0
	v_add_f32_e32 v4, v0, v1
	v_pk_mul_f32 v[0:1], v[8:9], v[8:9]
	s_nop 0
	v_add_f32_e32 v0, v4, v0
	v_add_f32_e32 v0, v0, v1
	v_cndmask_b32_e32 v1, v185, v188, vcc
	v_lshlrev_b32_e32 v1, 2, v1
	ds_bpermute_b32 v1, v1, v0
	v_cmp_lt_i32_e32 vcc, v189, v187
	s_waitcnt lgkmcnt(0)
	v_add_f32_e32 v0, v0, v1
	v_cndmask_b32_e32 v1, v185, v189, vcc
	v_lshlrev_b32_e32 v1, 2, v1
	ds_bpermute_b32 v1, v1, v0
	v_cmp_lt_i32_e32 vcc, v190, v187
	s_waitcnt lgkmcnt(0)
	v_add_f32_e32 v0, v0, v1
	v_cndmask_b32_e32 v1, v185, v190, vcc
	v_lshlrev_b32_e32 v1, 2, v1
	ds_bpermute_b32 v1, v1, v0
	s_waitcnt lgkmcnt(0)
	v_add_f32_e32 v0, v0, v1
	v_fmamk_f32 v0, v0, 0x3b000000, v182
	v_cmp_gt_f32_e32 vcc, s56, v0
	v_mul_f32_e32 v1, 0x4b800000, v0
	s_nop 0
	v_cndmask_b32_e32 v0, v0, v1, vcc
	v_rsq_f32_e32 v0, v0
	s_nop 0
	v_mul_f32_e32 v1, 0x45800000, v0
	v_cndmask_b32_e32 v16, v0, v1, vcc
	global_load_dwordx4 v[142:145], v32, s[0:1] offset:1792
	v_mul_f32_e32 v73, v73, v16
	v_mul_f32_e32 v69, v69, v16
	v_mul_f32_e32 v68, v68, v16
	v_mul_f32_e32 v67, v67, v16
	v_mul_f32_e32 v72, v72, v16
	v_mul_f32_e32 v71, v71, v16
	v_mul_f32_e32 v70, v70, v16
	v_mul_f32_e32 v51, v51, v16
	v_mul_f32_e32 v60, v60, v16
	v_mul_f32_e32 v56, v56, v16
	v_mul_f32_e32 v20, v20, v16
	v_mul_f32_e32 v22, v22, v16
	v_mul_f32_e32 v21, v21, v16
	v_mul_f32_e32 v10, v10, v16
	v_mul_f32_e32 v12, v12, v16
	v_mul_f32_e32 v13, v13, v16
	s_waitcnt vmcnt(15)
	v_mul_f32_e32 v0, v204, v69
	s_waitcnt vmcnt(14)
	v_mul_f32_e32 v4, v208, v73
	v_mul_f32_e32 v1, v205, v68
	v_mul_f32_e32 v67, v206, v67
	v_mul_f32_e32 v2, v65, v16
	v_mul_f32_e32 v5, v209, v72
	v_mul_f32_e32 v65, v207, v2
	v_cvt_pk_bf16_f32 v2, v4, v5
	v_cvt_pk_bf16_f32 v4, v0, v1
	v_lshl_add_u64 v[0:1], s[8:9], 0, v[108:109]
	v_lshl_add_u64 v[0:1], v[0:1], 0, s[28:29]
	v_lshl_add_u64 v[0:1], v[0:1], 0, v[132:133]
	v_mul_f32_e32 v6, v210, v71
	v_mul_f32_e32 v7, v211, v70
	v_cvt_pk_bf16_f32 v3, v6, v7
	v_cvt_pk_bf16_f32 v5, v67, v65
	global_store_dwordx4 v[0:1], v[2:5], off
	v_mul_f32_e32 v6, v66, v16
	v_mul_f32_e32 v7, v63, v16
	s_waitcnt vmcnt(14)
	v_mul_f32_e32 v51, v51, v212
	v_mul_f32_e32 v2, v45, v16
	v_mul_f32_e32 v45, v2, v213
	v_mul_f32_e32 v2, v40, v16
	v_mul_f32_e32 v40, v2, v214
	v_mul_f32_e32 v2, v35, v16
	v_mul_f32_e32 v5, v2, v215
	s_waitcnt vmcnt(13)
	v_mul_f32_e32 v6, v6, v216
	v_mul_f32_e32 v7, v7, v217
	v_mul_f32_e32 v60, v60, v218
	v_mul_f32_e32 v56, v56, v219
	v_cvt_pk_bf16_f32 v2, v6, v7
	v_cvt_pk_bf16_f32 v3, v60, v56
	v_cvt_pk_bf16_f32 v4, v51, v45
	v_cvt_pk_bf16_f32 v5, v40, v5
	global_store_dwordx4 v[0:1], v[2:5], off offset:128
	v_mul_f32_e32 v45, v46, v16
	v_mul_f32_e32 v6, v64, v16
	v_mul_f32_e32 v7, v61, v16
	v_mul_f32_e32 v35, v57, v16
	v_mul_f32_e32 v40, v52, v16
	s_waitcnt vmcnt(13)
	v_mul_f32_e32 v45, v45, v220
	v_mul_f32_e32 v2, v41, v16
	v_mul_f32_e32 v41, v2, v221
	v_mul_f32_e32 v2, v36, v16
	v_mul_f32_e32 v36, v2, v222
	v_mul_f32_e32 v2, v30, v16
	v_mul_f32_e32 v5, v2, v223
	s_waitcnt vmcnt(12)
	v_mul_f32_e32 v6, v6, v224
	v_mul_f32_e32 v7, v7, v225
	v_mul_f32_e32 v35, v35, v226
	v_mul_f32_e32 v40, v40, v227
	v_cvt_pk_bf16_f32 v2, v6, v7
	v_cvt_pk_bf16_f32 v3, v35, v40
	v_cvt_pk_bf16_f32 v4, v45, v41
	v_cvt_pk_bf16_f32 v5, v36, v5
	global_store_dwordx4 v[0:1], v[2:5], off offset:256
	v_mul_f32_e32 v36, v42, v16
	v_mul_f32_e32 v6, v62, v16
	v_mul_f32_e32 v7, v58, v16
	v_mul_f32_e32 v30, v53, v16
	v_mul_f32_e32 v35, v47, v16
	s_waitcnt vmcnt(12)
	v_mul_f32_e32 v36, v36, v228
	v_mul_f32_e32 v2, v37, v16
	v_mul_f32_e32 v37, v2, v229
	v_mul_f32_e32 v2, v31, v16
	v_mul_f32_e32 v31, v2, v230
	v_mul_f32_e32 v2, v27, v16
	v_mul_f32_e32 v5, v2, v231
	s_waitcnt vmcnt(11)
	v_mul_f32_e32 v6, v6, v232
	v_mul_f32_e32 v7, v7, v233
	v_mul_f32_e32 v30, v30, v234
	v_mul_f32_e32 v35, v35, v235
	v_cvt_pk_bf16_f32 v2, v6, v7
	v_cvt_pk_bf16_f32 v3, v30, v35
	v_cvt_pk_bf16_f32 v4, v36, v37
	v_cvt_pk_bf16_f32 v5, v31, v5
	global_store_dwordx4 v[0:1], v[2:5], off offset:384
	v_mul_f32_e32 v31, v38, v16
	v_mul_f32_e32 v6, v59, v16
	v_mul_f32_e32 v7, v54, v16
	v_mul_f32_e32 v27, v48, v16
	v_mul_f32_e32 v30, v43, v16
	s_waitcnt vmcnt(11)
	v_mul_f32_e32 v31, v31, v236
	v_mul_f32_e32 v2, v33, v16
	v_mul_f32_e32 v33, v2, v237
	v_mul_f32_e32 v2, v28, v16
	v_mul_f32_e32 v28, v2, v238
	v_mul_f32_e32 v2, v24, v16
	v_mul_f32_e32 v5, v2, v239
	s_waitcnt vmcnt(10)
	v_mul_f32_e32 v6, v6, v240
	v_mul_f32_e32 v7, v7, v241
	v_mul_f32_e32 v27, v27, v242
	v_mul_f32_e32 v30, v30, v243
	v_cvt_pk_bf16_f32 v2, v6, v7
	v_cvt_pk_bf16_f32 v3, v27, v30
	v_cvt_pk_bf16_f32 v4, v31, v33
	v_cvt_pk_bf16_f32 v5, v28, v5
	global_store_dwordx4 v[0:1], v[2:5], off offset:512
	v_mul_f32_e32 v28, v34, v16
	v_mul_f32_e32 v6, v55, v16
	v_mul_f32_e32 v7, v49, v16
	v_mul_f32_e32 v24, v44, v16
	v_mul_f32_e32 v27, v39, v16
	s_waitcnt vmcnt(10)
	v_mul_f32_e32 v28, v28, v146
	v_mul_f32_e32 v2, v29, v16
	v_mul_f32_e32 v29, v2, v147
	v_mul_f32_e32 v2, v25, v16
	v_mul_f32_e32 v25, v2, v148
	v_mul_f32_e32 v2, v23, v16
	v_mul_f32_e32 v5, v2, v149
	s_waitcnt vmcnt(9)
	v_mul_f32_e32 v6, v6, v150
	v_mul_f32_e32 v7, v7, v151
	v_mul_f32_e32 v24, v24, v152
	v_mul_f32_e32 v27, v27, v153
	v_cvt_pk_bf16_f32 v2, v6, v7
	v_cvt_pk_bf16_f32 v3, v24, v27
	v_cvt_pk_bf16_f32 v4, v28, v29
	v_cvt_pk_bf16_f32 v5, v25, v5
	global_store_dwordx4 v[0:1], v[2:5], off offset:640
	v_mul_f32_e32 v6, v50, v16
	v_mul_f32_e32 v7, v26, v16
	s_waitcnt vmcnt(9)
	v_mul_f32_e32 v20, v20, v168
	v_mul_f32_e32 v2, v19, v16
	v_mul_f32_e32 v19, v2, v169
	v_mul_f32_e32 v2, v18, v16
	v_mul_f32_e32 v18, v2, v170
	v_mul_f32_e32 v2, v17, v16
	v_mul_f32_e32 v5, v2, v171
	s_waitcnt vmcnt(8)
	v_mul_f32_e32 v6, v6, v172
	v_mul_f32_e32 v7, v7, v173
	v_mul_f32_e32 v22, v22, v174
	v_mul_f32_e32 v21, v21, v175
	v_cvt_pk_bf16_f32 v2, v6, v7
	v_cvt_pk_bf16_f32 v3, v22, v21
	v_cvt_pk_bf16_f32 v4, v20, v19
	v_cvt_pk_bf16_f32 v5, v18, v5
	global_store_dwordx4 v[0:1], v[2:5], off offset:768
	v_mul_f32_e32 v6, v14, v16
	v_mul_f32_e32 v7, v15, v16
	s_mov_b64 s[0:1], 0
	s_waitcnt vmcnt(8)
	v_mul_f32_e32 v10, v10, v176
	v_mul_f32_e32 v2, v11, v16
	v_mul_f32_e32 v11, v2, v177
	v_mul_f32_e32 v2, v8, v16
	v_mul_f32_e32 v8, v2, v178
	v_mul_f32_e32 v2, v9, v16
	v_mul_f32_e32 v5, v2, v179
	s_waitcnt vmcnt(7)
	v_mul_f32_e32 v6, v6, v142
	v_mul_f32_e32 v7, v7, v143
	v_mul_f32_e32 v12, v12, v144
	v_mul_f32_e32 v13, v13, v145
	v_cvt_pk_bf16_f32 v2, v6, v7
	v_cvt_pk_bf16_f32 v3, v12, v13
	v_cvt_pk_bf16_f32 v4, v10, v11
	v_cvt_pk_bf16_f32 v5, v8, v5
	global_store_dwordx4 v[0:1], v[2:5], off offset:896
	s_barrier
